# cross-attention softmax/P.V: exp+cvt per 16-key slice interleaved between k-step-major P.V MFMAs, V fragments in two refilled banks (strategy 8)
# baseline (speedup 1.0000x reference)
; __device__ __forceinline__ unsigned cvtpk(float lo, float hi) { f32x2_t v = {lo, hi}; bf16x2_t b = __builtin_convertvector(v, bf16x2_t); return __builtin_bit_cast(unsigned, b); }
; #define ATT_MMAG(F, dvb) do { _Pragma("unroll") for (int j = 0; j < 4; ++j) o[dvb] = __builtin_amdgcn_mfma_f32_32x32x16_bf16(F[j], pb[j >> 1][j & 1], o[dvb], 0, 0, 0); } while (0)
; template <bool DIFF> ...
;     ...
;             const float d0 = c0 - m_run, d1 = c1 - m_run;
;             float rs0 = 0.f, rs1 = 0.f;
; #pragma unroll
;             for (int r = 0; r < 16; ++r) { s0[r] = __builtin_amdgcn_exp2f(__builtin_fmaf(s0[r], sc2, d0)); s1[r] = __builtin_amdgcn_exp2f(__builtin_fmaf(s1[r], sc2, d1)); rs0 += s0[r]; rs1 += s1[r]; }
;             l_run += rs0 + rs1;
;             bf16x8 pb[2][2];
; #pragma unroll
;             for (int g = 0; g < 2; ++g) {
;                 u32x4 w0, w1;
;                 w0.x = cvtpk(s0[8 * g], s0[8 * g + 1]); w0.y = cvtpk(s0[8 * g + 2], s0[8 * g + 3]); w0.z = cvtpk(s0[8 * g + 4], s0[8 * g + 5]); w0.w = cvtpk(s0[8 * g + 6], s0[8 * g + 7]);
;                 w1.x = cvtpk(s1[8 * g], s1[8 * g + 1]); w1.y = cvtpk(s1[8 * g + 2], s1[8 * g + 3]); w1.z = cvtpk(s1[8 * g + 4], s1[8 * g + 5]); w1.w = cvtpk(s1[8 * g + 6], s1[8 * g + 7]);
;                 pb[0][g] = __builtin_bit_cast(bf16x8, w0); pb[1][g] = __builtin_bit_cast(bf16x8, w1);
;             }
;             __builtin_amdgcn_sched_barrier(0);
;             ATT_MMAG(fa, 0); ATT_LOADG(fa, 2); __builtin_amdgcn_sched_barrier(0); ATT_MMAG(fb, 1); ATT_LOADG(fb, 3); __builtin_amdgcn_sched_barrier(0); ATT_MMAG(fa, 2); ATT_MMAG(fb, 3);
.LBB0_252:
	v_sub_f32_e32 v236, 0, v208
	v_fmamk_f32 v98, v98, 0x3db8aa3b, v236
	v_fmamk_f32 v99, v99, 0x3db8aa3b, v236
	v_fmamk_f32 v100, v100, 0x3db8aa3b, v236
	v_fmamk_f32 v101, v101, 0x3db8aa3b, v236
	v_fmamk_f32 v102, v102, 0x3db8aa3b, v236
	v_fmamk_f32 v103, v103, 0x3db8aa3b, v236
	v_fmamk_f32 v104, v104, 0x3db8aa3b, v236
	v_fmamk_f32 v105, v105, 0x3db8aa3b, v236
	v_exp_f32_e32 v98, v98
	v_exp_f32_e32 v99, v99
	v_exp_f32_e32 v100, v100
	v_exp_f32_e32 v101, v101
	v_exp_f32_e32 v102, v102
	v_exp_f32_e32 v103, v103
	v_exp_f32_e32 v104, v104
	v_exp_f32_e32 v105, v105
	v_pk_add_f32 v[238:239], v[98:99], v[100:101]
	v_pk_add_f32 v[238:239], v[238:239], v[102:103]
	v_pk_add_f32 v[238:239], v[238:239], v[104:105]
	v_cvt_pk_bf16_f32 v98, v98, v99
	v_cvt_pk_bf16_f32 v99, v100, v101
	v_cvt_pk_bf16_f32 v100, v102, v103
	v_cvt_pk_bf16_f32 v101, v104, v105
	s_waitcnt lgkmcnt(8)
	s_nop 1
	v_mfma_f32_32x32x16_bf16 v[50:65], v[146:149], v[98:101], v[50:65]
	v_fmamk_f32 v106, v106, 0x3db8aa3b, v236
	v_fmamk_f32 v107, v107, 0x3db8aa3b, v236
	v_fmamk_f32 v108, v108, 0x3db8aa3b, v236
	v_fmamk_f32 v109, v109, 0x3db8aa3b, v236
	v_fmamk_f32 v110, v110, 0x3db8aa3b, v236
	v_fmamk_f32 v111, v111, 0x3db8aa3b, v236
	v_fmamk_f32 v112, v112, 0x3db8aa3b, v236
	v_mfma_f32_32x32x16_bf16 v[34:49], v[150:153], v[98:101], v[34:49]
	v_fmamk_f32 v113, v113, 0x3db8aa3b, v236
	v_exp_f32_e32 v106, v106
	v_exp_f32_e32 v107, v107
	v_exp_f32_e32 v108, v108
	v_exp_f32_e32 v109, v109
	v_exp_f32_e32 v110, v110
	v_exp_f32_e32 v111, v111
	v_mfma_f32_32x32x16_bf16 v[18:33], v[154:157], v[98:101], v[18:33]
	v_exp_f32_e32 v112, v112
	v_exp_f32_e32 v113, v113
	v_pk_add_f32 v[238:239], v[238:239], v[106:107]
	v_pk_add_f32 v[238:239], v[238:239], v[108:109]
	v_pk_add_f32 v[238:239], v[238:239], v[110:111]
	v_pk_add_f32 v[238:239], v[238:239], v[112:113]
	v_cvt_pk_bf16_f32 v106, v106, v107
	v_mfma_f32_32x32x16_bf16 v[2:17], v[158:161], v[98:101], v[2:17]
	ds_read_b64_tr_b16 v[146:147], v205 offset:18432
	ds_read_b64_tr_b16 v[148:149], v205 offset:23040
	ds_read_b64_tr_b16 v[150:151], v205 offset:18496
	ds_read_b64_tr_b16 v[152:153], v205 offset:23104
	ds_read_b64_tr_b16 v[154:155], v205 offset:18560
	ds_read_b64_tr_b16 v[156:157], v205 offset:23168
	ds_read_b64_tr_b16 v[158:159], v205 offset:18624
	ds_read_b64_tr_b16 v[160:161], v205 offset:23232
	v_cvt_pk_bf16_f32 v107, v108, v109
	v_cvt_pk_bf16_f32 v108, v110, v111
	v_cvt_pk_bf16_f32 v109, v112, v113
	s_waitcnt lgkmcnt(8)
	s_nop 1
	v_mfma_f32_32x32x16_bf16 v[50:65], v[162:165], v[106:109], v[50:65]
	v_fmamk_f32 v82, v82, 0x3db8aa3b, v236
	v_fmamk_f32 v83, v83, 0x3db8aa3b, v236
	v_fmamk_f32 v84, v84, 0x3db8aa3b, v236
	v_fmamk_f32 v85, v85, 0x3db8aa3b, v236
	v_fmamk_f32 v86, v86, 0x3db8aa3b, v236
	v_fmamk_f32 v87, v87, 0x3db8aa3b, v236
	v_fmamk_f32 v88, v88, 0x3db8aa3b, v236
	v_mfma_f32_32x32x16_bf16 v[34:49], v[166:169], v[106:109], v[34:49]
	v_fmamk_f32 v89, v89, 0x3db8aa3b, v236
	v_exp_f32_e32 v82, v82
	v_exp_f32_e32 v83, v83
	v_exp_f32_e32 v84, v84
	v_exp_f32_e32 v85, v85
	v_exp_f32_e32 v86, v86
	v_exp_f32_e32 v87, v87
	v_mfma_f32_32x32x16_bf16 v[18:33], v[170:173], v[106:109], v[18:33]
	v_exp_f32_e32 v88, v88
	v_exp_f32_e32 v89, v89
	v_pk_add_f32 v[238:239], v[238:239], v[82:83]
	v_pk_add_f32 v[238:239], v[238:239], v[84:85]
	v_pk_add_f32 v[238:239], v[238:239], v[86:87]
	v_pk_add_f32 v[238:239], v[238:239], v[88:89]
	v_cvt_pk_bf16_f32 v82, v82, v83
	v_mfma_f32_32x32x16_bf16 v[2:17], v[174:177], v[106:109], v[2:17]
	ds_read_b64_tr_b16 v[162:163], v205 offset:27648
	ds_read_b64_tr_b16 v[164:165], v205 offset:32256
	ds_read_b64_tr_b16 v[166:167], v205 offset:27712
	ds_read_b64_tr_b16 v[168:169], v205 offset:32320
	ds_read_b64_tr_b16 v[170:171], v205 offset:27776
	ds_read_b64_tr_b16 v[172:173], v205 offset:32384
	ds_read_b64_tr_b16 v[174:175], v205 offset:27840
	ds_read_b64_tr_b16 v[176:177], v205 offset:32448
	v_cvt_pk_bf16_f32 v83, v84, v85
	v_cvt_pk_bf16_f32 v84, v86, v87
	v_cvt_pk_bf16_f32 v85, v88, v89
	s_waitcnt lgkmcnt(8)
	s_nop 1
	v_mfma_f32_32x32x16_bf16 v[50:65], v[146:149], v[82:85], v[50:65]
	v_fmamk_f32 v90, v90, 0x3db8aa3b, v236
	v_fmamk_f32 v91, v91, 0x3db8aa3b, v236
	v_fmamk_f32 v92, v92, 0x3db8aa3b, v236
	v_fmamk_f32 v93, v93, 0x3db8aa3b, v236
	v_fmamk_f32 v94, v94, 0x3db8aa3b, v236
	v_fmamk_f32 v95, v95, 0x3db8aa3b, v236
	v_fmamk_f32 v96, v96, 0x3db8aa3b, v236
	v_mfma_f32_32x32x16_bf16 v[34:49], v[150:153], v[82:85], v[34:49]
	v_fmamk_f32 v97, v97, 0x3db8aa3b, v236
	v_exp_f32_e32 v90, v90
	v_exp_f32_e32 v91, v91
	v_exp_f32_e32 v92, v92
	v_exp_f32_e32 v93, v93
	v_exp_f32_e32 v94, v94
	v_exp_f32_e32 v95, v95
	v_mfma_f32_32x32x16_bf16 v[18:33], v[154:157], v[82:85], v[18:33]
	v_exp_f32_e32 v96, v96
	v_exp_f32_e32 v97, v97
	v_pk_add_f32 v[238:239], v[238:239], v[90:91]
	v_pk_add_f32 v[238:239], v[238:239], v[92:93]
	v_pk_add_f32 v[238:239], v[238:239], v[94:95]
	v_pk_add_f32 v[238:239], v[238:239], v[96:97]
	v_cvt_pk_bf16_f32 v90, v90, v91
	v_mfma_f32_32x32x16_bf16 v[2:17], v[158:161], v[82:85], v[2:17]
	v_cvt_pk_bf16_f32 v91, v92, v93
	v_cvt_pk_bf16_f32 v92, v94, v95
	v_cvt_pk_bf16_f32 v93, v96, v97
	s_waitcnt lgkmcnt(0)
	s_nop 1
	v_mfma_f32_32x32x16_bf16 v[50:65], v[162:165], v[90:93], v[50:65]
	v_mfma_f32_32x32x16_bf16 v[34:49], v[166:169], v[90:93], v[34:49]
	v_mfma_f32_32x32x16_bf16 v[18:33], v[170:173], v[90:93], v[18:33]
	v_mfma_f32_32x32x16_bf16 v[2:17], v[174:177], v[90:93], v[2:17]
	v_add_f32_e32 v238, v238, v239
	s_cmp_lg_u32 s15, 4
	v_add_f32_e32 v203, v203, v238
	s_cbranch_scc0 .LBB0_250

; template <bool DIFF> ...
;     ...
;             for (int kq = 0; kq < NKS; kq += 4) {
;                 bf16x8 ka0[4], ka1[4], qq[4];
; #pragma unroll
;                 for (int j = 0; j < 4; ++j) {
;                     if (DIFF) { const int ko = 256 * l32 + 16 * (((c << 3) + 2 * j + hi) ^ (((l32 & 3) << 2) | ((l32 >> 2) & 3)));
;                         ka0[j] = *(LAS const bf16x8*)(kb + ko); ka1[j] = *(LAS const bf16x8*)(kb + 8192 + ko); }
;                     else { ka0[j] = *(LAS const bf16x8*)(ka + (kq + j) * 32); ka1[j] = *(LAS const bf16x8*)(ka + 32 * KSTR + (kq + j) * 32); }
;                     qq[j] = DIFF ? qf[DIFF ? j : 0] : *(LAS const bf16x8*)(qa + (kq + j) * 32); }
;                 __builtin_amdgcn_sched_barrier(0);
; #pragma unroll
;                 for (int j = 0; j < 4; ++j) { s0 = __builtin_amdgcn_mfma_f32_32x32x16_bf16(ka0[j], qq[j], s0, 0, 0, 0); s1 = __builtin_amdgcn_mfma_f32_32x32x16_bf16(ka1[j], qq[j], s1, 0, 0, 0); }
;             }
;             float c0 = 0.f, c1 = 0.f;
;             if (DIFF) {
;                 c0 = sl2 * (float)(64 * kt - wrow); c1 = sl2 * (float)(64 * kt + 32 - wrow);
;                 if (64 * kt + 64 > wrow) {
;                     asm volatile("" ::: "memory");
;                     const int irel = wrow + l32 - 64 * kt - hi * 4;
; #pragma unroll
;                     for (int r = 0; r < 16; ++r) { const int cr = (r >> 2) * 8 + (r & 3); if (cr > irel) s0[r] = -INFINITY; if (cr + 32 > irel) s1[r] = -INFINITY; }
;                 }
;             }
;             LAS const unsigned char* va = vb + (hi * 4 + ((lane & 15) >> 2)) * VSTR + (DIFF ? 0 : c * 256) + (((lane >> 4) & 1) * 16 + 4 * (lane & 3)) * 2;
;             bf16x8 fa[4], fb[4];
;             const int vq = (lane & 15) >> 2, vp = lane & 3, vg1 = (lane >> 4) & 1;
;             const int vs0 = 256 * (hi * 4 + vq) + 16 * ((2 * vg1 + (vp >> 1)) ^ hi) + 8 * (vp & 1), vs1 = 256 * (hi * 4 + 8 + vq) + 16 * ((2 * vg1 + (vp >> 1)) ^ (hi + 2)) + 8 * (vp & 1);
;     ...
;             float mx0 = s0[0], mx1 = s1[0];
; #pragma unroll
;             for (int r = 1; r < 16; r += 2) { mx0 = fmaxf(fmaxf(mx0, s0[r]), s0[r + 1 < 16 ? r + 1 : r]); mx1 = fmaxf(fmaxf(mx1, s1[r]), s1[r + 1 < 16 ? r + 1 : r]); }
;             float mx = fmaxf(__builtin_fmaf(mx0, sc2, c0), __builtin_fmaf(mx1, sc2, c1));
;             mx = fmaxf(mx, __shfl_xor(mx, 32));
.LBB0_256:
	v_add_u32_e32 v176, v146, v200
	v_add_u32_e32 v147, v0, v200
	v_add_u32_e32 v164, 0x11400, v176
	v_add_u32_e32 v168, 0x11420, v176
	ds_read_b128 v[148:151], v147
	ds_read_b128 v[152:155], v147 offset:32
	ds_read_b128 v[156:159], v147 offset:16896
	ds_read_b128 v[160:163], v147 offset:16928
	ds_read_b128 v[164:167], v164
	ds_read_b128 v[168:171], v168
	ds_read_b128 v[172:175], v147 offset:64
	ds_read_b128 v[210:213], v147 offset:96
	ds_read_b128 v[214:217], v147 offset:16960
	ds_read_b128 v[218:221], v147 offset:16992
	v_add_u32_e32 v177, 0x11440, v176
	v_add_u32_e32 v147, 0x11460, v176
	ds_read_b128 v[222:225], v177
	ds_read_b128 v[226:229], v147
	s_waitcnt lgkmcnt(7)
	v_mfma_f32_32x32x16_bf16 v[98:113], v[148:151], v[164:167], v[98:113]
	s_add_i32 s18, s18, 4
	v_add_u32_e32 v146, 0x80, v146
	v_add_u32_e32 v0, 0x80, v0
	s_cmp_gt_u32 s18, 11
	v_mfma_f32_32x32x16_bf16 v[82:97], v[156:159], v[164:167], v[82:97]
	s_waitcnt lgkmcnt(6)
	v_mfma_f32_32x32x16_bf16 v[98:113], v[152:155], v[168:171], v[98:113]
	v_mfma_f32_32x32x16_bf16 v[82:97], v[160:163], v[168:171], v[82:97]
	s_waitcnt lgkmcnt(1)
	v_mfma_f32_32x32x16_bf16 v[98:113], v[172:175], v[222:225], v[98:113]
	v_mfma_f32_32x32x16_bf16 v[82:97], v[214:217], v[222:225], v[82:97]
	s_waitcnt lgkmcnt(0)
	v_mfma_f32_32x32x16_bf16 v[98:113], v[210:213], v[226:229], v[98:113]
	v_mfma_f32_32x32x16_bf16 v[82:97], v[218:221], v[226:229], v[82:97]
	s_cbranch_scc0 .LBB0_256
	s_nop 9
	v_max_f32_e32 v0, v99, v99
	v_max_f32_e32 v146, v98, v98
	v_max_f32_e32 v0, v146, v0
	v_max_f32_e32 v146, v83, v83
	v_max_f32_e32 v147, v82, v82
	v_max_f32_e32 v146, v147, v146
	v_max3_f32 v0, v0, v100, v101
	v_max3_f32 v146, v146, v84, v85
	v_max3_f32 v0, v0, v102, v103
	v_max3_f32 v146, v146, v86, v87
	v_max3_f32 v0, v0, v104, v105
	v_max3_f32 v146, v146, v88, v89
	v_max3_f32 v0, v0, v106, v107
	v_max3_f32 v146, v146, v90, v91
	v_max3_f32 v0, v0, v108, v109
	v_max3_f32 v146, v146, v92, v93
	v_max3_f32 v0, v0, v110, v111
	v_max3_f32 v146, v146, v94, v95
	v_max3_f32 v0, v0, v112, v113
	v_max3_f32 v146, v146, v96, v97
	v_fma_f32 v0, v0, s44, 0
	v_fma_f32 v146, v146, s44, 0
	v_max_f32_e32 v0, v0, v146
	ds_bpermute_b32 v209, v202, v0
	ds_read_b64_tr_b16 v[146:147], v205 offset:0
	ds_read_b64_tr_b16 v[148:149], v205 offset:4608
	ds_read_b64_tr_b16 v[150:151], v205 offset:64
	ds_read_b64_tr_b16 v[152:153], v205 offset:4672
	ds_read_b64_tr_b16 v[154:155], v205 offset:128
	ds_read_b64_tr_b16 v[156:157], v205 offset:4736
	ds_read_b64_tr_b16 v[158:159], v205 offset:192
	ds_read_b64_tr_b16 v[160:161], v205 offset:4800
	ds_read_b64_tr_b16 v[162:163], v205 offset:9216
	ds_read_b64_tr_b16 v[164:165], v205 offset:13824
	ds_read_b64_tr_b16 v[166:167], v205 offset:9280
	ds_read_b64_tr_b16 v[168:169], v205 offset:13888
	ds_read_b64_tr_b16 v[170:171], v205 offset:9344
	ds_read_b64_tr_b16 v[172:173], v205 offset:13952
	ds_read_b64_tr_b16 v[174:175], v205 offset:9408
	ds_read_b64_tr_b16 v[176:177], v205 offset:14016
	s_waitcnt lgkmcnt(15)
	v_max_f32_e32 v209, v209, v209
	v_max_f32_e32 v0, v0, v209
	v_cmp_gt_f32_e32 vcc, v0, v208
	s_cbranch_vccz .LBB0_252
	v_max_f32_e32 v0, v0, v0
	v_max_f32_e32 v209, v208, v208
	v_max_f32_e32 v209, v209, v0
	v_sub_f32_e32 v0, v208, v209
	v_exp_f32_e32 v0, v0
	v_mov_b32_e32 v208, v209
	v_pk_mul_f32 v[64:65], v[64:65], v[0:1] op_sel_hi:[1,0]
	v_pk_mul_f32 v[62:63], v[62:63], v[0:1] op_sel_hi:[1,0]
	v_pk_mul_f32 v[60:61], v[60:61], v[0:1] op_sel_hi:[1,0]
	v_pk_mul_f32 v[58:59], v[58:59], v[0:1] op_sel_hi:[1,0]
	v_pk_mul_f32 v[56:57], v[56:57], v[0:1] op_sel_hi:[1,0]
	v_pk_mul_f32 v[54:55], v[54:55], v[0:1] op_sel_hi:[1,0]
	v_pk_mul_f32 v[52:53], v[52:53], v[0:1] op_sel_hi:[1,0]
	v_pk_mul_f32 v[50:51], v[50:51], v[0:1] op_sel_hi:[1,0]
	v_pk_mul_f32 v[48:49], v[48:49], v[0:1] op_sel_hi:[1,0]
	v_pk_mul_f32 v[46:47], v[46:47], v[0:1] op_sel_hi:[1,0]
	v_pk_mul_f32 v[44:45], v[44:45], v[0:1] op_sel_hi:[1,0]
	v_pk_mul_f32 v[42:43], v[42:43], v[0:1] op_sel_hi:[1,0]
	v_pk_mul_f32 v[40:41], v[40:41], v[0:1] op_sel_hi:[1,0]
	v_pk_mul_f32 v[38:39], v[38:39], v[0:1] op_sel_hi:[1,0]
	v_pk_mul_f32 v[36:37], v[36:37], v[0:1] op_sel_hi:[1,0]
	v_pk_mul_f32 v[34:35], v[34:35], v[0:1] op_sel_hi:[1,0]
	v_pk_mul_f32 v[32:33], v[32:33], v[0:1] op_sel_hi:[1,0]
	v_pk_mul_f32 v[30:31], v[30:31], v[0:1] op_sel_hi:[1,0]
	v_pk_mul_f32 v[28:29], v[28:29], v[0:1] op_sel_hi:[1,0]
	v_pk_mul_f32 v[26:27], v[26:27], v[0:1] op_sel_hi:[1,0]
	v_pk_mul_f32 v[24:25], v[24:25], v[0:1] op_sel_hi:[1,0]
	v_pk_mul_f32 v[22:23], v[22:23], v[0:1] op_sel_hi:[1,0]
	v_pk_mul_f32 v[20:21], v[20:21], v[0:1] op_sel_hi:[1,0]
	v_pk_mul_f32 v[18:19], v[18:19], v[0:1] op_sel_hi:[1,0]
	v_pk_mul_f32 v[16:17], v[16:17], v[0:1] op_sel_hi:[1,0]
	v_pk_mul_f32 v[14:15], v[14:15], v[0:1] op_sel_hi:[1,0]
	v_pk_mul_f32 v[12:13], v[12:13], v[0:1] op_sel_hi:[1,0]
	v_pk_mul_f32 v[10:11], v[10:11], v[0:1] op_sel_hi:[1,0]
	v_pk_mul_f32 v[8:9], v[8:9], v[0:1] op_sel_hi:[1,0]
	v_pk_mul_f32 v[6:7], v[6:7], v[0:1] op_sel_hi:[1,0]
	v_pk_mul_f32 v[4:5], v[4:5], v[0:1] op_sel_hi:[1,0]
	v_pk_mul_f32 v[2:3], v[2:3], v[0:1] op_sel_hi:[1,0]
	v_mul_f32_e32 v203, v203, v0
	s_branch .LBB0_252
